# phase-4 queue order re-derived from the new item costs (longest first): sample attention, weight converts, prompt attention, sample ssd_out, ssd state tiles
# speedup vs baseline: 1.0057x; 1.0039x over previous
.LBB0_774:
	s_or_b64 exec, exec, s[2:3]
	s_waitcnt lgkmcnt(0)
	s_barrier
	ds_read_b32 v0, v182
	s_movk_i32 s2, 0x476
	s_waitcnt lgkmcnt(0)
	v_cmp_lt_i32_e32 vcc, s2, v0
	v_readfirstlane_b32 s18, v0
	s_mov_b64 s[2:3], -1
	s_cbranch_vccnz .LBB0_769
	s_movk_i32 s98, 0x457
	s_cmpk_ge_u32 s18, 16
	s_cselect_b32 s98, -16, s98
	s_cmpk_ge_u32 s18, 567
	s_cselect_b32 s98, 496, s98
	s_cmpk_ge_u32 s18, 615
	s_cselect_b32 s98, -64, s98
	s_cmpk_ge_u32 s18, 1127
	s_cselect_b32 s98, 0, s98
	s_add_i32 s18, s18, s98
	s_cmpk_gt_i32 s18, 0x46
	s_cbranch_scc0 .LBB0_1018
	s_cmpk_gt_u32 s18, 0x226
	s_cbranch_scc0 .LBB0_1015
	s_cmpk_gt_u32 s18, 0x426
	s_cbranch_scc0 .LBB0_1029
	s_cmpk_gt_u32 s18, 0x446
	s_cbranch_scc0 .LBB0_1030
	s_cmpk_gt_u32 s18, 0x456
	s_cbranch_scc0 .LBB0_1031
	s_cmpk_gt_u32 s18, 0x466
	s_cbranch_scc0 .LBB0_877
	v_mov_b32_e32 v148, v252
	s_nop 0
	v_and_b32_e32 v149, 63, v148
	v_readfirstlane_b32 s6, v148
	s_ashr_i32 s30, s6, 6
	v_cmp_gt_u32_e32 vcc, 32, v149
	v_cmp_lt_u32_e64 s[40:41], 31, v149
	s_barrier
	s_and_saveexec_b64 s[2:3], s[40:41]
	s_xor_b64 s[2:3], exec, s[2:3]
	s_ashr_i32 s31, s30, 31
	s_or_saveexec_b64 s[2:3], s[2:3]
	s_add_i32 s8, s18, 0xfffffb99
	s_lshl_b32 s10, s8, 5
	s_add_i32 s9, s10, 0x8000
	v_mov_b32_e32 v0, 0
	v_mov_b64_e32 v[2:3], s[30:31]
	s_xor_b64 exec, exec, s[2:3]
	s_cbranch_execz .LBB0_787
	s_load_dwordx2 s[4:5], s[0:1], 0x60
	v_or_b32_e32 v0, s9, v149
	s_ashr_i32 s31, s30, 31
	v_lshlrev_b64 v[2:3], 5, v[0:1]
	s_lshl_b64 s[36:37], s[30:31], 2
	v_lshl_add_u64 v[2:3], s[12:13], 0, v[2:3]
	s_waitcnt lgkmcnt(0)
	s_add_u32 s4, s4, s36
	v_lshl_add_u64 v[2:3], v[2:3], 0, s[36:37]
	s_addc_u32 s5, s5, s37
	global_load_dword v0, v[2:3], off
	s_nop 0
	global_load_dword v2, v1, s[4:5]
	s_mov_b32 s4, 0x41a00000
	s_waitcnt vmcnt(0)
	v_add_f32_e32 v0, v0, v2
	v_cmp_nlt_f32_e64 s[40:41], s4, v0
	s_and_saveexec_b64 s[4:5], s[40:41]
	s_cbranch_execz .LBB0_786
	v_mul_f32_e32 v2, 0x3fb8aa3b, v0
	v_rndne_f32_e32 v3, v2
	s_mov_b32 s7, 0x3fb8aa3b
	v_sub_f32_e32 v4, v2, v3
	v_fma_f32 v2, v0, s7, -v2
	v_fmac_f32_e32 v2, 0x32a5705f, v0
	v_add_f32_e32 v2, v4, v2
	v_cvt_i32_f32_e32 v3, v3
	v_exp_f32_e32 v2, v2
	s_mov_b32 s7, 0xc2ce8ed0
	v_cmp_ngt_f32_e64 s[40:41], s7, v0
	s_mov_b32 s7, 0x3f2aaaab
	v_ldexp_f32 v2, v2, v3
	v_cndmask_b32_e64 v2, 0, v2, s[40:41]
	v_cmp_nlt_f32_e64 s[40:41], s80, v0
	s_nop 1
	v_cndmask_b32_e64 v0, v183, v2, s[40:41]
	v_add_f32_e32 v4, 1.0, v0
	v_add_f32_e32 v2, -1.0, v4
	v_sub_f32_e32 v3, v2, v4
	v_add_f32_e32 v3, 1.0, v3
	v_sub_f32_e32 v2, v0, v2
	v_add_f32_e32 v5, v2, v3
	v_frexp_mant_f32_e32 v6, v4
	v_cvt_f64_f32_e32 v[2:3], v4
	v_frexp_exp_i32_f64_e32 v2, v[2:3]
	v_cmp_gt_f32_e64 s[40:41], s7, v6
	s_mov_b32 s7, 0x3f317218
	s_nop 0
	v_subbrev_co_u32_e64 v10, s[40:41], 0, v2, s[40:41]
	v_sub_u32_e32 v2, 0, v10
	v_ldexp_f32 v3, v4, v2
	v_add_f32_e32 v4, -1.0, v3
	v_add_f32_e32 v6, 1.0, v3
	v_ldexp_f32 v2, v5, v2
	v_add_f32_e32 v5, 1.0, v4
	v_add_f32_e32 v7, -1.0, v6
	v_sub_f32_e32 v5, v3, v5
	v_sub_f32_e32 v3, v3, v7
	v_add_f32_e32 v5, v2, v5
	v_add_f32_e32 v2, v2, v3
	v_add_f32_e32 v11, v6, v2
	v_rcp_f32_e32 v13, v11
	v_sub_f32_e32 v3, v6, v11
	v_add_f32_e32 v12, v2, v3
	v_add_f32_e32 v3, v4, v5
	v_mul_f32_e32 v15, v3, v13
	v_sub_f32_e32 v2, v4, v3
	v_mul_f32_e32 v4, v11, v15
	v_fma_f32 v6, v15, v11, -v4
	v_fmac_f32_e32 v6, v15, v12
	v_add_f32_e32 v14, v5, v2
	v_add_f32_e32 v2, v4, v6
	v_sub_f32_e32 v5, v3, v2
	v_pk_add_f32 v[8:9], v[2:3], v[4:5] neg_lo:[0,1] neg_hi:[0,1]
	v_mov_b32_e32 v7, v2
	v_pk_add_f32 v[2:3], v[8:9], v[6:7] neg_lo:[0,1] neg_hi:[0,1]
	s_nop 0
	v_add_f32_e32 v3, v14, v3
	v_add_f32_e32 v2, v2, v3
	v_add_f32_e32 v3, v5, v2
	v_mul_f32_e32 v14, v13, v3
	v_mul_f32_e32 v4, v11, v14
	v_fma_f32 v6, v14, v11, -v4
	v_fmac_f32_e32 v6, v14, v12
	v_sub_f32_e32 v5, v5, v3
	v_add_f32_e32 v11, v2, v5
	v_add_f32_e32 v2, v4, v6
	v_sub_f32_e32 v5, v3, v2
	v_pk_add_f32 v[8:9], v[2:3], v[4:5] neg_lo:[0,1] neg_hi:[0,1]
	v_mov_b32_e32 v7, v2
	v_pk_add_f32 v[2:3], v[8:9], v[6:7] neg_lo:[0,1] neg_hi:[0,1]
	s_nop 0
	v_add_f32_e32 v3, v11, v3
	v_add_f32_e32 v2, v2, v3
	v_add_f32_e32 v3, v15, v14
	v_add_f32_e32 v2, v5, v2
	v_sub_f32_e32 v4, v3, v15
	v_mul_f32_e32 v2, v13, v2
	v_sub_f32_e32 v4, v14, v4
	v_add_f32_e32 v4, v4, v2
	v_add_f32_e32 v6, v3, v4
	v_mul_f32_e32 v7, v6, v6
	v_fmamk_f32 v2, v7, 0x3e9b6dac, v178
	v_fmaak_f32 v165, v7, v2, 0x3f2aaada
	v_cvt_f32_i32_e32 v2, v10
	v_sub_f32_e32 v3, v6, v3
	v_sub_f32_e32 v3, v4, v3
	v_ldexp_f32 v8, v3, 1
	v_mul_f32_e32 v3, v6, v7
	v_ldexp_f32 v5, v6, 1
	v_pk_mul_f32 v[6:7], v[2:3], v[164:165]
	s_nop 0
	v_fma_f32 v4, v2, s7, -v6
	v_fmac_f32_e32 v4, 0xb102e308, v2
	v_pk_add_f32 v[2:3], v[6:7], v[4:5]
	s_mov_b32 s7, 0x7f800000
	v_sub_f32_e32 v5, v3, v5
	v_sub_f32_e32 v5, v7, v5
	v_add_f32_e32 v9, v8, v5
	v_mov_b32_e32 v8, v6
	v_pk_add_f32 v[6:7], v[2:3], v[6:7] neg_lo:[0,1] neg_hi:[0,1]
	v_pk_add_f32 v[10:11], v[2:3], v[8:9]
	v_mov_b32_e32 v5, v2
	v_mov_b32_e32 v7, v11
	v_pk_add_f32 v[12:13], v[4:5], v[6:7] neg_lo:[0,1] neg_hi:[0,1]
	v_pk_add_f32 v[4:5], v[4:5], v[6:7]
	v_mov_b32_e32 v8, v9
	v_pk_add_f32 v[6:7], v[4:5], v[2:3] op_sel:[1,0] op_sel_hi:[0,1] neg_lo:[0,1] neg_hi:[0,1]
	v_pk_add_f32 v[14:15], v[10:11], v[6:7] op_sel_hi:[1,0] neg_lo:[0,1] neg_hi:[0,1]
	v_mov_b32_e32 v10, v11
	v_mov_b32_e32 v11, v5
	v_pk_mov_b32 v[6:7], v[2:3], v[6:7] op_sel:[1,0]
	v_mov_b32_e32 v9, v2
	v_pk_add_f32 v[6:7], v[10:11], v[6:7] neg_lo:[0,1] neg_hi:[0,1]
	v_mov_b32_e32 v14, v12
	v_pk_add_f32 v[2:3], v[8:9], v[6:7] neg_lo:[0,1] neg_hi:[0,1]
	v_mov_b32_e32 v13, v5
	v_pk_add_f32 v[6:7], v[14:15], v[2:3]
	v_cmp_neq_f32_e64 s[40:41], s7, v0
	v_pk_add_f32 v[8:9], v[6:7], v[6:7] op_sel:[0,1] op_sel_hi:[1,0]
	s_mov_b32 s7, 0x33800000
	v_pk_add_f32 v[4:5], v[4:5], v[8:9] op_sel:[1,0] op_sel_hi:[0,1]
	v_mov_b32_e32 v7, v4
	v_pk_add_f32 v[10:11], v[6:7], v[12:13] neg_lo:[0,1] neg_hi:[0,1]
	v_mov_b32_e32 v3, v8
	v_sub_f32_e32 v5, v6, v10
	v_pk_add_f32 v[2:3], v[2:3], v[10:11] neg_lo:[0,1] neg_hi:[0,1]
	v_sub_f32_e32 v5, v12, v5
	v_add_f32_e32 v2, v2, v5
	v_add_f32_e32 v2, v2, v3
	v_add_f32_e32 v2, v4, v2
	v_cndmask_b32_e64 v2, v183, v2, s[40:41]
	v_cmp_lt_f32_e64 s[40:41], |v0|, s7
	s_nop 1
	v_cndmask_b32_e64 v0, v2, v0, s[40:41]
